# phase dispatch: kind/layer from packed scalar constants instead of two vector table loads waited on after every grid barrier
# speedup vs baseline: 1.0126x; 1.0126x over previous
; #define LAS __attribute__((address_space(3)))
; __device__ __forceinline__ int tid_() { int t = (int)threadIdx.x; asm volatile("" : "+v"(t)); return t & 511; }
; __device__ __forceinline__ int bid_() { int b = (int)blockIdx.x; asm volatile("" : "+s"(b)); return b; }
; __device__ __forceinline__ int gdim_() { int g = (int)gridDim.x; asm volatile("" : "+s"(g)); return g; }
; DI float rs_of(float ss, float inv_n) { return __builtin_amdgcn_rsqf(ss * inv_n + EPS); }
; DI float sum16(const float* p) { const f32x4 a = *(const f32x4*)p, b = *(const f32x4*)(p + 4), c = *(const f32x4*)(p + 8), d = *(const f32x4*)(p + 12); const f32x4 s = (a + b) + (c + d); return (s[0] + s[1]) + (s[2] + s[3]); }
; DI void final_norm(const Params& P) {
;     unsigned char* ws = P.ws; const int gt = bid_() * 512 + tid_(), NT = gdim_() * 512;
;     const float* X = (const float*)(ws + O_X); const float* SS = (const float*)(ws + O_ST); const float* g = P.in[I_NFIN];
; #pragma unroll 4
;     for (int i = gt; i < T * 256; i += NT) { const int row = i >> 8, c4 = (i & 255) * 4; const float rs = rs_of(sum16(SS + (size_t)row * 16), 1.f / 1024.f);
;         const f32x4 v = *(const f32x4*)(X + (size_t)row * DM + c4) * *(const f32x4*)(g + c4) * rs; *(f32x4*)(P.out + OUT_Y + (size_t)row * DM + c4) = v; }
; DI void run_phase(const Params& P, int ph, LAS unsigned char* lds) {
;     const int kind = PH_KIND[ph], l = PH_LAYER[ph]; unsigned char* ws = P.ws;
;     GemmD g; bool is_gemm = true;
;     g.A = (const bf16_t*)(ws + O_XB); g.lda = 1024; g.ldb = 1024; g.a_pn_off = 0; g.nM = 66; g.nN = 4; g.K = 1024; g.Bt = nullptr;
;     switch (kind) {
.LBB0_78:
	v_readlane_b32 s0, v254, 1
	v_readlane_b32 s1, v254, 2
	s_lshr_b32 s8, s95, 3
	s_and_b32 s48, s95, 7
	s_lshl_b32 s48, s48, 3
	s_mov_b32 s2, 0x7020100
	s_mov_b32 s3, 0x4030908
	s_cmp_eq_u32 s8, 1
	s_cselect_b32 s2, 0x2010605, s2
	s_cselect_b32 s3, 0x4030b0a, s3
	s_cmp_eq_u32 s8, 2
	s_cselect_b32 s2, 0x2010605, s2
	s_cselect_b32 s3, 0xf0e0d0c, s3
	s_cmp_eq_u32 s8, 3
	s_cselect_b32 s2, 0x5040310, s2
	s_cselect_b32 s3, 0x11020106, s3
	s_cmp_eq_u32 s8, 4
	s_cselect_b32 s2, 0x15141312, s2
	s_cselect_b32 s3, 0x6050403, s3
	s_cmp_eq_u32 s8, 5
	s_cselect_b32 s2, 0x16, s2
	s_cselect_b32 s3, 0x0, s3
	s_lshr_b64 s[2:3], s[2:3], s48
	s_and_b32 s63, s2, 0xff
	s_cmp_gt_u32 s95, 9
	s_cselect_b32 s62, 1, 0
	s_cmp_gt_u32 s95, 17
	s_cselect_b32 s8, 1, 0
	s_add_i32 s62, s62, s8
	s_cmp_gt_u32 s95, 28
	s_cselect_b32 s8, 1, 0
	s_add_i32 s62, s62, s8
	v_mov_b32_e32 v0, s63
	v_mov_b32_e32 v1, s62
	s_waitcnt lgkmcnt(0)
	s_load_dwordx2 s[26:27], s[0:1], 0x158
	s_mov_b64 s[2:3], 0
	v_writelane_b32 v255, s2, 25
	s_mov_b64 s[4:5], -1
	s_mov_b64 s[88:89], 0
	v_writelane_b32 v255, s3, 26
	s_waitcnt lgkmcnt(0)
	s_add_u32 s60, s26, 0xedc0000
	s_addc_u32 s61, s27, 0
	v_cmp_lt_i32_sdwa s[2:3], v0, v186 src0_sel:WORD_0 src1_sel:DWORD
	v_readfirstlane_b32 s63, v0
	s_and_b64 vcc, exec, s[2:3]
	v_readfirstlane_b32 s62, v1
	s_cbranch_vccnz .LBB0_96
	s_and_b32 s2, 0xffff, s63
	s_cmp_gt_i32 s2, 16
	s_cbranch_scc0 .LBB0_156
	v_writelane_b32 v255, s4, 27
	s_cmp_gt_i32 s2, 19
	s_nop 0
	v_writelane_b32 v255, s5, 28
	s_mov_b64 s[4:5], -1
	s_cbranch_scc0 .LBB0_169
	s_cmp_gt_i32 s2, 20
	s_cbranch_scc0 .LBB0_163
	s_cmp_gt_i32 s2, 21
	s_mov_b64 s[6:7], -1
	s_cbranch_scc0 .LBB0_94
	s_cmp_eq_u32 s2, 22
	s_cbranch_scc0 .LBB0_93
	v_readlane_b32 s16, v254, 0
	v_mov_b32_e32 v0, v167
	s_lshl_b32 s14, s16, 9
	v_and_b32_e32 v3, 0x1ff, v0
	v_or_b32_e32 v1, s14, v3
	s_mov_b32 s3, 0x420000
	s_load_dword s18, s[50:51], 0x0
	v_cmp_gt_i32_e32 vcc, s3, v1
	s_waitcnt lgkmcnt(0)
	s_and_saveexec_b64 s[4:5], vcc
	s_cbranch_execz .LBB0_92
	s_lshl_b32 s3, s18, 9
	v_cvt_f32_u32_e32 v0, s3
	s_add_u32 s6, s26, 0xabc0000
	s_addc_u32 s7, s27, 0
	s_add_u32 s8, s26, 0x10ec0000
	v_rcp_iflag_f32_e32 v0, v0
	s_addc_u32 s9, s27, 0
	s_add_i32 s14, s14, s3
	v_or_b32_e32 v2, s14, v3
	v_mul_f32_e32 v0, 0x4f7ffffe, v0
	v_cvt_u32_f32_e32 v0, v0
	s_mov_b32 s14, 0x420000
	v_cmp_gt_i32_e32 vcc, s14, v2
	v_max_i32_e32 v4, 0x420000, v2
	s_sub_i32 s14, 0, s3
	v_addc_co_u32_e64 v2, s[38:39], 0, v2, vcc
	v_sub_u32_e32 v2, v4, v2
	v_mul_lo_u32 v4, s14, v0
	v_mul_hi_u32 v4, v0, v4
	v_add_u32_e32 v0, v0, v4
	v_mul_hi_u32 v0, v2, v0
	v_mul_lo_u32 v4, v0, s3
	v_sub_u32_e32 v2, v2, v4
	v_add_u32_e32 v4, 1, v0
	v_cmp_le_u32_e64 s[38:39], s3, v2
	s_load_dwordx2 s[10:11], s[0:1], 0xa0
	s_load_dwordx2 s[12:13], s[0:1], 0x150
	v_cndmask_b32_e64 v0, v0, v4, s[38:39]
	v_subrev_u32_e32 v4, s3, v2
	v_cndmask_b32_e64 v2, v2, v4, s[38:39]
	v_add_u32_e32 v4, 1, v0
	v_cmp_le_u32_e64 s[38:39], s3, v2
	v_cndmask_b32_e64 v5, 1, 2, vcc
	s_nop 0
	v_cndmask_b32_e64 v0, v0, v4, s[38:39]
	v_add_u32_e32 v2, v5, v0
	v_and_b32_e32 v2, 3, v2
	v_cmp_ne_u32_e64 s[38:39], 0, v2
	s_and_saveexec_b64 s[14:15], s[38:39]
	s_cbranch_execz .LBB0_89
	v_lshlrev_b32_e32 v3, 2, v3
	v_lshl_or_b32 v3, s16, 11, v3
	s_lshl_b32 s19, s18, 11
	s_mov_b64 s[16:17], 0
